# phase-0 x->bf16 stream: four iterations of loads in flight (scalar-guarded, original loop kept as fallback)
# baseline (speedup 1.0000x reference)
; DI u16* XB(const Params& p) { return (u16*)(PWS(p) + WS_XB); }
; DI unsigned pack2(float a, float b) { f32x2v v = {a, b}; hwbf16x2 r = __builtin_convertvector(v, hwbf16x2); return __builtin_bit_cast(unsigned, r); }
; DI void phase0(const Params& p, char* smem) {
;     ...
;     const float* x = p.in[0];
;     u16* xb = XB(p);
;     for (size_t i = gtid; i < (size_t)T * D / 8; i += gsz) {
;       const float* s8 = x + i * 8;
;       float4 a, b;
;       a.x = __builtin_nontemporal_load(s8); a.y = __builtin_nontemporal_load(s8 + 1); a.z = __builtin_nontemporal_load(s8 + 2); a.w = __builtin_nontemporal_load(s8 + 3);
;       b.x = __builtin_nontemporal_load(s8 + 4); b.y = __builtin_nontemporal_load(s8 + 5); b.z = __builtin_nontemporal_load(s8 + 6); b.w = __builtin_nontemporal_load(s8 + 7);
;       uint4 o; o.x = pack2(a.x, a.y); o.y = pack2(a.z, a.w); o.z = pack2(b.x, b.y); o.w = pack2(b.z, b.w);
;       *(uint4*)(xb + i * 8) = o;
;     }
.LBB0_1159:
	s_or_b64 exec, exec, s[0:1]
	v_readlane_b32 s4, v254, 33
	v_readlane_b32 s5, v254, 34
	v_readlane_b32 s6, v254, 35
	v_readlane_b32 s7, v254, 36
	v_mov_b32 v0, s6
	v_mov_b32 v4, s7
	s_mov_b64 s[0:1], 0x400000
	v_readfirstlane_b32 s4, v0
	v_readfirstlane_b32 s5, v4
	v_cmp_gt_u64_e32 vcc, s[0:1], v[2:3]
	v_lshlrev_b64 v[4:5], 5, v[34:35]
	s_and_saveexec_b64 s[0:1], vcc
	v_readlane_b32 s8, v253, 22
	v_readlane_b32 s10, v253, 26
	v_readlane_b32 s9, v253, 23
	v_readlane_b32 s11, v253, 27
	s_cbranch_execz .LBB0_1162
	v_readlane_b32 s6, v253, 20
	s_add_u32 s4, s4, s6
	v_readlane_b32 s6, v253, 21
	s_addc_u32 s5, s5, s6
	v_lshl_add_u64 v[6:7], v[34:35], 4, s[4:5]
	v_readlane_b32 s4, v253, 24
	v_readlane_b32 s5, v253, 25
	v_mov_b64_e32 v[10:11], v[2:3]
	s_nop 0
	v_lshl_add_u64 v[8:9], s[4:5], 0, v[4:5]
	s_mov_b64 s[4:5], 0
	s_cmp_lg_u32 s74, 0x20000
	s_cbranch_scc1 .LBB0_1161
	s_cmp_lg_u32 s75, 0
	s_cbranch_scc1 .LBB0_1161
	s_branch .Lxcvt4
.LBB0_1161:
	global_load_dwordx4 v[12:15], v[8:9], off offset:-16 nt
	global_load_dwordx4 v[16:19], v[8:9], off nt
	v_lshl_add_u64 v[10:11], v[10:11], 0, s[74:75]
	s_mov_b64 s[6:7], 0x3fffff
	v_cmp_lt_u64_e32 vcc, s[6:7], v[10:11]
	v_lshl_add_u64 v[8:9], v[8:9], 0, s[10:11]
	s_or_b64 s[4:5], vcc, s[4:5]
	s_waitcnt vmcnt(0)
	v_cvt_pk_bf16_f32 v12, v12, v13
	v_cvt_pk_bf16_f32 v13, v14, v15
	v_cvt_pk_bf16_f32 v14, v16, v17
	v_cvt_pk_bf16_f32 v15, v18, v19
	global_store_dwordx4 v[6:7], v[12:15], off offset:-12
	v_lshl_add_u64 v[6:7], v[6:7], 0, s[8:9]
	s_andn2_b64 exec, exec, s[4:5]
	s_cbranch_execnz .LBB0_1161
	s_branch .LBB0_1162
.Lxcvt4:
	v_lshl_add_u64 v[132:133], v[8:9], 0, s[10:11]
	v_lshl_add_u64 v[134:135], v[132:133], 0, s[10:11]
	v_lshl_add_u64 v[136:137], v[134:135], 0, s[10:11]
	global_load_dwordx4 v[100:103], v[8:9], off offset:-16 nt
	global_load_dwordx4 v[104:107], v[8:9], off nt
	global_load_dwordx4 v[108:111], v[132:133], off offset:-16 nt
	global_load_dwordx4 v[112:115], v[132:133], off nt
	global_load_dwordx4 v[116:119], v[134:135], off offset:-16 nt
	global_load_dwordx4 v[120:123], v[134:135], off nt
	global_load_dwordx4 v[124:127], v[136:137], off offset:-16 nt
	global_load_dwordx4 v[128:131], v[136:137], off nt
	v_lshl_add_u64 v[8:9], v[136:137], 0, s[10:11]
	v_lshl_add_u64 v[10:11], v[10:11], 0, s[74:75]
	v_lshl_add_u64 v[10:11], v[10:11], 0, s[74:75]
	v_lshl_add_u64 v[10:11], v[10:11], 0, s[74:75]
	v_lshl_add_u64 v[10:11], v[10:11], 0, s[74:75]
	s_mov_b64 s[6:7], 0x3fffff
	v_cmp_lt_u64_e32 vcc, s[6:7], v[10:11]
	s_or_b64 s[4:5], vcc, s[4:5]
	s_waitcnt vmcnt(0)
	v_cvt_pk_bf16_f32 v100, v100, v101
	v_cvt_pk_bf16_f32 v101, v102, v103
	v_cvt_pk_bf16_f32 v102, v104, v105
	v_cvt_pk_bf16_f32 v103, v106, v107
	global_store_dwordx4 v[6:7], v[100:103], off offset:-12
	v_lshl_add_u64 v[6:7], v[6:7], 0, s[8:9]
	v_cvt_pk_bf16_f32 v108, v108, v109
	v_cvt_pk_bf16_f32 v109, v110, v111
	v_cvt_pk_bf16_f32 v110, v112, v113
	v_cvt_pk_bf16_f32 v111, v114, v115
	global_store_dwordx4 v[6:7], v[108:111], off offset:-12
	v_lshl_add_u64 v[6:7], v[6:7], 0, s[8:9]
	v_cvt_pk_bf16_f32 v116, v116, v117
	v_cvt_pk_bf16_f32 v117, v118, v119
	v_cvt_pk_bf16_f32 v118, v120, v121
	v_cvt_pk_bf16_f32 v119, v122, v123
	global_store_dwordx4 v[6:7], v[116:119], off offset:-12
	v_lshl_add_u64 v[6:7], v[6:7], 0, s[8:9]
	v_cvt_pk_bf16_f32 v124, v124, v125
	v_cvt_pk_bf16_f32 v125, v126, v127
	v_cvt_pk_bf16_f32 v126, v128, v129
	v_cvt_pk_bf16_f32 v127, v130, v131
	global_store_dwordx4 v[6:7], v[124:127], off offset:-12
	v_lshl_add_u64 v[6:7], v[6:7], 0, s[8:9]
	s_andn2_b64 exec, exec, s[4:5]
	s_cbranch_execnz .Lxcvt4
